# v5 + MLA row-sum via two independent v_pk_add_f32 accumulators (v[14:15], v[242:243])
# speedup vs baseline: 1.0070x; 1.0070x over previous
; #define LAS __attribute__((address_space(3)))
; #define MFMA32(a, b, c) __builtin_amdgcn_mfma_f32_32x32x16_bf16((a), (b), (c), 0, 0, 0)
; DI s16x4 trread(LAS const char* p) { return __builtin_bit_cast(s16x4, __builtin_amdgcn_ds_read_tr16_b64_v4i16((LAS v4i16_t*)p)); }
; DI bf16x8 cat8(s16x4 lo, s16x4 hi) { return __builtin_shufflevector(lo, hi, 0, 1, 2, 3, 4, 5, 6, 7); }
; DI void mla_phase(const Args& A, LAS unsigned char* lds, int i, const int wv) {
;     ...
;             float ls = 0.f;
; #pragma unroll
;             for (int kt = 0; kt < 4; ++kt)
; #pragma unroll
;                 for (int rg = 0; rg < 16; ++rg) { p[kt][rg] = __builtin_amdgcn_exp2f(p[kt][rg]); ls += p[kt][rg]; }
;             l += ls;
; #pragma unroll
;             for (int kt = 0; kt < 4; ++kt)
; #pragma unroll
;                 for (int s = 0; s < 2; ++s) { const bf16x8 pb = pack8(p[kt], s);
; #pragma unroll
;                     for (int dt = 0; dt < 2; ++dt) { LAS const char* ad = (LAS const char*)vbp + (32 * kt + 16 * s + 4 * h + q_) * 144 + (32 * dt + 16 * blk) * 2 + 8 * p_;
;                         const bf16x8 va = cat8(trread(ad), trread(ad + 8 * 144)); o[dt] = MFMA32(va, pb, o[dt]); } }
.Lmla_a_norescale:
	v_exp_f32_e32 v112, v112
	v_exp_f32_e32 v113, v113
	v_exp_f32_e32 v114, v114
	v_exp_f32_e32 v115, v115
	v_exp_f32_e32 v116, v116
	v_exp_f32_e32 v117, v117
	v_exp_f32_e32 v118, v118
	v_exp_f32_e32 v119, v119
	v_pk_add_f32 v[14:15], v[112:113], v[114:115]
	v_pk_add_f32 v[242:243], v[116:117], v[118:119]
	v_cvt_pk_bf16_f32 v10, v112, v113
	v_cvt_pk_bf16_f32 v11, v114, v115
	v_cvt_pk_bf16_f32 v12, v116, v117
	v_cvt_pk_bf16_f32 v13, v118, v119
	ds_read_b64_tr_b16 v[116:117], v182 offset:28928
	ds_read_b64_tr_b16 v[118:119], v182 offset:30080
	v_exp_f32_e32 v120, v120
	v_exp_f32_e32 v121, v121
	v_exp_f32_e32 v122, v122
	v_exp_f32_e32 v123, v123
	v_exp_f32_e32 v124, v124
	v_exp_f32_e32 v125, v125
	v_exp_f32_e32 v126, v126
	v_exp_f32_e32 v127, v127
	v_pk_add_f32 v[14:15], v[14:15], v[120:121]
	v_pk_add_f32 v[242:243], v[242:243], v[122:123]
	v_pk_add_f32 v[14:15], v[14:15], v[124:125]
	v_pk_add_f32 v[242:243], v[242:243], v[126:127]
	v_cvt_pk_bf16_f32 v112, v120, v121
	v_cvt_pk_bf16_f32 v113, v122, v123
	v_cvt_pk_bf16_f32 v114, v124, v125
	v_cvt_pk_bf16_f32 v115, v126, v127
	ds_read_b64_tr_b16 v[120:121], v182 offset:28992
	ds_read_b64_tr_b16 v[122:123], v182 offset:30144
	s_nop 0
	v_mfma_f32_32x32x16_bf16 v[32:47], v[2:5], v[10:13], v[32:47]
	ds_read_b64_tr_b16 v[2:3], v182 offset:31232
	ds_read_b64_tr_b16 v[4:5], v182 offset:32384
	v_exp_f32_e32 v96, v96
	v_exp_f32_e32 v97, v97
	v_exp_f32_e32 v98, v98
	v_exp_f32_e32 v99, v99
	v_exp_f32_e32 v100, v100
	v_exp_f32_e32 v101, v101
	v_mfma_f32_32x32x16_bf16 v[16:31], v[6:9], v[10:13], v[16:31]
	ds_read_b64_tr_b16 v[6:7], v182 offset:31296
	ds_read_b64_tr_b16 v[8:9], v182 offset:32448
	v_exp_f32_e32 v102, v102
	v_exp_f32_e32 v103, v103
	v_pk_add_f32 v[14:15], v[14:15], v[96:97]
	v_pk_add_f32 v[242:243], v[242:243], v[98:99]
	v_pk_add_f32 v[14:15], v[14:15], v[100:101]
	v_pk_add_f32 v[242:243], v[242:243], v[102:103]
	v_cvt_pk_bf16_f32 v124, v96, v97
	v_cvt_pk_bf16_f32 v125, v98, v99
	v_cvt_pk_bf16_f32 v126, v100, v101
	v_cvt_pk_bf16_f32 v127, v102, v103
	s_waitcnt lgkmcnt(6)
	v_mfma_f32_32x32x16_bf16 v[32:47], v[116:119], v[112:115], v[32:47]
	ds_read_b64_tr_b16 v[116:117], v182 offset:33536
	ds_read_b64_tr_b16 v[118:119], v182 offset:34688
	v_exp_f32_e32 v104, v104
	v_exp_f32_e32 v105, v105
	v_exp_f32_e32 v106, v106
	v_exp_f32_e32 v107, v107
	v_exp_f32_e32 v108, v108
	v_exp_f32_e32 v109, v109
	v_exp_f32_e32 v110, v110
	v_exp_f32_e32 v111, v111
	v_pk_add_f32 v[14:15], v[14:15], v[104:105]
	v_pk_add_f32 v[242:243], v[242:243], v[106:107]
	s_waitcnt lgkmcnt(6)
	v_mfma_f32_32x32x16_bf16 v[16:31], v[120:123], v[112:115], v[16:31]
	ds_read_b64_tr_b16 v[120:121], v182 offset:33600
	ds_read_b64_tr_b16 v[122:123], v182 offset:34752
	v_pk_add_f32 v[14:15], v[14:15], v[108:109]
	v_pk_add_f32 v[242:243], v[242:243], v[110:111]
	v_cvt_pk_bf16_f32 v10, v104, v105
	v_cvt_pk_bf16_f32 v11, v106, v107
	v_cvt_pk_bf16_f32 v12, v108, v109
	v_cvt_pk_bf16_f32 v13, v110, v111
	s_waitcnt lgkmcnt(6)
	v_mfma_f32_32x32x16_bf16 v[32:47], v[2:5], v[124:127], v[32:47]
	ds_read_b64_tr_b16 v[2:3], v182 offset:35840
	ds_read_b64_tr_b16 v[4:5], v182 offset:36992
	v_exp_f32_e32 v80, v80
	v_exp_f32_e32 v81, v81
	v_exp_f32_e32 v82, v82
	v_exp_f32_e32 v83, v83
	v_exp_f32_e32 v84, v84
	v_exp_f32_e32 v85, v85
	v_exp_f32_e32 v86, v86
	v_exp_f32_e32 v87, v87
	v_pk_add_f32 v[14:15], v[14:15], v[80:81]
	v_pk_add_f32 v[242:243], v[242:243], v[82:83]
	s_waitcnt lgkmcnt(6)
	v_mfma_f32_32x32x16_bf16 v[16:31], v[6:9], v[124:127], v[16:31]
	ds_read_b64_tr_b16 v[6:7], v182 offset:35904
	ds_read_b64_tr_b16 v[8:9], v182 offset:37056
	v_pk_add_f32 v[14:15], v[14:15], v[84:85]
	v_pk_add_f32 v[242:243], v[242:243], v[86:87]
	v_cvt_pk_bf16_f32 v112, v80, v81
	v_cvt_pk_bf16_f32 v113, v82, v83
	v_cvt_pk_bf16_f32 v114, v84, v85
	v_cvt_pk_bf16_f32 v115, v86, v87
	s_waitcnt lgkmcnt(6)
	v_mfma_f32_32x32x16_bf16 v[32:47], v[116:119], v[10:13], v[32:47]
	ds_read_b64_tr_b16 v[116:117], v182 offset:38144
	ds_read_b64_tr_b16 v[118:119], v182 offset:39296
	v_exp_f32_e32 v88, v88
	v_exp_f32_e32 v89, v89
	v_exp_f32_e32 v90, v90
	v_exp_f32_e32 v91, v91
	v_exp_f32_e32 v92, v92
	v_exp_f32_e32 v93, v93
	v_exp_f32_e32 v94, v94
	v_exp_f32_e32 v95, v95
	v_pk_add_f32 v[14:15], v[14:15], v[88:89]
	v_pk_add_f32 v[242:243], v[242:243], v[90:91]
	s_waitcnt lgkmcnt(6)
	v_mfma_f32_32x32x16_bf16 v[16:31], v[120:123], v[10:13], v[16:31]
	ds_read_b64_tr_b16 v[120:121], v182 offset:38208
	ds_read_b64_tr_b16 v[122:123], v182 offset:39360
	v_pk_add_f32 v[14:15], v[14:15], v[92:93]
	v_pk_add_f32 v[242:243], v[242:243], v[94:95]
	v_cvt_pk_bf16_f32 v124, v88, v89
	v_cvt_pk_bf16_f32 v125, v90, v91
	v_cvt_pk_bf16_f32 v126, v92, v93
	v_cvt_pk_bf16_f32 v127, v94, v95
	s_waitcnt lgkmcnt(6)
	v_mfma_f32_32x32x16_bf16 v[32:47], v[2:5], v[112:115], v[32:47]
	ds_read_b64_tr_b16 v[2:3], v182 offset:40448
	ds_read_b64_tr_b16 v[4:5], v182 offset:41600
	v_exp_f32_e32 v64, v64
	v_exp_f32_e32 v65, v65
	v_exp_f32_e32 v66, v66
	v_exp_f32_e32 v67, v67
	v_exp_f32_e32 v68, v68
	v_exp_f32_e32 v69, v69
	v_exp_f32_e32 v70, v70
	v_exp_f32_e32 v71, v71
	v_pk_add_f32 v[14:15], v[14:15], v[64:65]
	v_pk_add_f32 v[242:243], v[242:243], v[66:67]
	s_waitcnt lgkmcnt(6)
	v_mfma_f32_32x32x16_bf16 v[16:31], v[6:9], v[112:115], v[16:31]
	ds_read_b64_tr_b16 v[6:7], v182 offset:40512
	ds_read_b64_tr_b16 v[8:9], v182 offset:41664
	v_pk_add_f32 v[14:15], v[14:15], v[68:69]
	v_pk_add_f32 v[242:243], v[242:243], v[70:71]
	v_cvt_pk_bf16_f32 v10, v64, v65
	v_cvt_pk_bf16_f32 v11, v66, v67
	v_cvt_pk_bf16_f32 v12, v68, v69
	v_cvt_pk_bf16_f32 v13, v70, v71
	s_waitcnt lgkmcnt(6)
	v_mfma_f32_32x32x16_bf16 v[32:47], v[116:119], v[124:127], v[32:47]
	ds_read_b64_tr_b16 v[116:117], v182 offset:42752
	ds_read_b64_tr_b16 v[118:119], v182 offset:43904
	v_exp_f32_e32 v72, v72
	v_exp_f32_e32 v73, v73
	v_exp_f32_e32 v74, v74
	v_exp_f32_e32 v75, v75
	v_exp_f32_e32 v76, v76
	v_exp_f32_e32 v77, v77
	v_exp_f32_e32 v78, v78
	v_exp_f32_e32 v79, v79
	v_pk_add_f32 v[14:15], v[14:15], v[72:73]
	v_pk_add_f32 v[242:243], v[242:243], v[74:75]
	s_waitcnt lgkmcnt(6)
	v_mfma_f32_32x32x16_bf16 v[16:31], v[120:123], v[124:127], v[16:31]
	ds_read_b64_tr_b16 v[120:121], v182 offset:42816
	ds_read_b64_tr_b16 v[122:123], v182 offset:43968
	v_pk_add_f32 v[14:15], v[14:15], v[76:77]
	v_pk_add_f32 v[242:243], v[242:243], v[78:79]
	v_cvt_pk_bf16_f32 v112, v72, v73
	v_cvt_pk_bf16_f32 v113, v74, v75
	v_cvt_pk_bf16_f32 v114, v76, v77
	v_cvt_pk_bf16_f32 v115, v78, v79
	s_nop 0
	s_waitcnt lgkmcnt(6)
	v_mfma_f32_32x32x16_bf16 v[32:47], v[2:5], v[10:13], v[32:47]
	v_pk_add_f32 v[14:15], v[14:15], v[242:243]
	s_waitcnt lgkmcnt(4)
	v_mfma_f32_32x32x16_bf16 v[16:31], v[6:9], v[10:13], v[16:31]
	v_add_f32_e32 v14, v14, v15
	s_waitcnt lgkmcnt(2)
	v_mfma_f32_32x32x16_bf16 v[32:47], v[116:119], v[112:115], v[32:47]
	v_add_f32_e32 v0, v0, v14
	s_waitcnt lgkmcnt(0)
	v_mfma_f32_32x32x16_bf16 v[16:31], v[120:123], v[112:115], v[16:31]
	s_add_i32 s7, s7, 1
	s_cmp_eq_u32 s7, 64
	s_cbranch_scc1 .Lmla_a_nost
; DI void mla_phase(const Args& A, LAS unsigned char* lds, int i, const int wv) {
;     ...
;             if (j + 1 < 64) MLA_ST((j + 1) & 1);
	s_bitcmp1_b32 s7, 0
	s_cselect_b32 s2, 0xb000, 0
	v_add3_u32 v183, s2, v251, v252
	s_waitcnt vmcnt(4)
	ds_write_b128 v183, v[128:131]
	v_add3_u32 v242, s2, v239, v172
	s_waitcnt vmcnt(3)
	ds_write_b128 v242, v[132:135]
	v_add3_u32 v183, s2, v173, v174
	s_waitcnt vmcnt(2)
	ds_write_b128 v183, v[136:139]
	v_add_u32_e32 v242, s2, v246
	v_add_u32_e32 v183, v242, v175
	v_add_u32_e32 v242, v242, v234
	s_waitcnt vmcnt(1)
	ds_write_b128 v183, v[140:143] offset:26624
	s_waitcnt vmcnt(0)
	ds_write_b128 v242, v[144:147] offset:26624
